# GEMM: first K-loop iteration of every tile peeled with C=0 MFMAs; the 128 accumulator-zeroing moves per tile removed
# baseline (speedup 1.0000x reference)
.LBB0_140:
	s_add_u32 s0, s70, 0x80
	s_addc_u32 s1, s71, 0
	s_add_u32 s70, s68, 0x100
	s_addc_u32 s71, s69, 0
	s_mov_b32 s40, 0
	s_add_i32 s72, s40, 2
	s_add_u32 s68, s0, 0x80
	s_addc_u32 s41, s1, 0
	s_add_i32 s73, 0, 0x10000
	v_add_u32_e32 v140, s73, v183
	ds_read_b128 v[128:131], v140
	ds_read_b128 v[132:135], v140 offset:1024
	ds_read_b128 v[136:139], v140 offset:2048
	ds_read_b128 v[140:143], v140 offset:3072
	s_cmp_eq_u32 s10, s40
	s_cselect_b32 s40, s64, s68
	s_cselect_b32 s41, s65, s41
	s_cselect_b32 s69, s67, s71
	s_cselect_b32 s68, s66, s70
	v_lshl_add_u64 v[176:177], s[0:1], 0, v[192:193]
	s_add_i32 m0, s76, 0xc000
	ds_read_b128 v[144:147], v239
	ds_read_b128 v[148:151], v239 offset:1024
	ds_read_b128 v[152:155], v239 offset:2048
	ds_read_b128 v[156:159], v239 offset:3072
	ds_read_b128 v[160:163], v239 offset:4096
	ds_read_b128 v[164:167], v239 offset:5120
	ds_read_b128 v[168:171], v239 offset:6144
	ds_read_b128 v[172:175], v239 offset:7168
	global_load_lds_dwordx4 v[176:177], off
	v_lshl_add_u64 v[176:177], s[0:1], 0, v[194:195]
	s_add_i32 m0, s76, 0xe000
	s_nop 0
	global_load_lds_dwordx4 v[176:177], off
	s_waitcnt lgkmcnt(8)
	s_barrier
	s_waitcnt lgkmcnt(0)
	s_waitcnt lgkmcnt(0)
	v_mfma_f32_16x16x32_bf16 v[124:127], v[128:131], v[144:147], 0
	v_mfma_f32_16x16x32_bf16 v[116:119], v[136:139], v[144:147], 0
	v_mfma_f32_16x16x32_bf16 v[108:111], v[128:131], v[152:155], 0
	v_mfma_f32_16x16x32_bf16 v[100:103], v[136:139], v[152:155], 0
	v_mfma_f32_16x16x32_bf16 v[92:95], v[128:131], v[160:163], 0
	v_mfma_f32_16x16x32_bf16 v[84:87], v[136:139], v[160:163], 0
	v_mfma_f32_16x16x32_bf16 v[76:79], v[128:131], v[168:171], 0
	v_mfma_f32_16x16x32_bf16 v[68:71], v[136:139], v[168:171], 0
	v_mfma_f32_16x16x32_bf16 v[124:127], v[132:135], v[148:151], v[124:127]
	v_mfma_f32_16x16x32_bf16 v[116:119], v[140:143], v[148:151], v[116:119]
	v_mfma_f32_16x16x32_bf16 v[108:111], v[132:135], v[156:159], v[108:111]
	v_mfma_f32_16x16x32_bf16 v[100:103], v[140:143], v[156:159], v[100:103]
	v_mfma_f32_16x16x32_bf16 v[92:95], v[132:135], v[164:167], v[92:95]
	v_mfma_f32_16x16x32_bf16 v[84:87], v[140:143], v[164:167], v[84:87]
	v_mfma_f32_16x16x32_bf16 v[76:79], v[132:135], v[172:175], v[76:79]
	v_mfma_f32_16x16x32_bf16 v[68:71], v[140:143], v[172:175], v[68:71]
	s_barrier
	s_add_i32 s80, 0, 0x14000
	s_add_i32 s73, s73, s33
	v_add_u32_e32 v204, s80, v183
	v_lshl_add_u64 v[208:209], s[68:69], 0, v[186:187]
	s_mov_b32 m0, s73
	ds_read_b128 v[176:179], v204
	ds_read_b128 v[196:199], v204 offset:1024
	ds_read_b128 v[200:203], v204 offset:2048
	ds_read_b128 v[204:207], v204 offset:3072
	global_load_lds_dwordx4 v[208:209], off
	v_lshl_add_u64 v[210:211], s[68:69], 0, v[190:191]
	s_add_i32 m0, s73, 0x2000
	s_nop 0
	global_load_lds_dwordx4 v[210:211], off
	s_barrier
	s_waitcnt lgkmcnt(0)
	s_waitcnt lgkmcnt(0)
	v_mfma_f32_16x16x32_bf16 v[120:123], v[176:179], v[144:147], 0
	v_mfma_f32_16x16x32_bf16 v[112:115], v[200:203], v[144:147], 0
	v_mfma_f32_16x16x32_bf16 v[104:107], v[176:179], v[152:155], 0
	v_mfma_f32_16x16x32_bf16 v[96:99], v[200:203], v[152:155], 0
	v_mfma_f32_16x16x32_bf16 v[88:91], v[176:179], v[160:163], 0
	v_mfma_f32_16x16x32_bf16 v[80:83], v[200:203], v[160:163], 0
	v_mfma_f32_16x16x32_bf16 v[72:75], v[176:179], v[168:171], 0
	v_mfma_f32_16x16x32_bf16 v[64:67], v[200:203], v[168:171], 0
	v_mfma_f32_16x16x32_bf16 v[120:123], v[196:199], v[148:151], v[120:123]
	v_mfma_f32_16x16x32_bf16 v[112:115], v[204:207], v[148:151], v[112:115]
	v_mfma_f32_16x16x32_bf16 v[104:107], v[196:199], v[156:159], v[104:107]
	v_mfma_f32_16x16x32_bf16 v[96:99], v[204:207], v[156:159], v[96:99]
	v_mfma_f32_16x16x32_bf16 v[88:91], v[196:199], v[164:167], v[88:91]
	v_mfma_f32_16x16x32_bf16 v[80:83], v[204:207], v[164:167], v[80:83]
	v_mfma_f32_16x16x32_bf16 v[72:75], v[196:199], v[172:175], v[72:75]
	v_mfma_f32_16x16x32_bf16 v[64:67], v[204:207], v[172:175], v[64:67]
	s_mov_b32 m0, s76
	v_lshl_add_u64 v[212:213], s[40:41], 0, v[184:185]
	s_barrier
	ds_read_b128 v[144:147], v239 offset:16384
	ds_read_b128 v[148:151], v239 offset:17408
	ds_read_b128 v[152:155], v239 offset:18432
	ds_read_b128 v[156:159], v239 offset:19456
	ds_read_b128 v[160:163], v239 offset:20480
	ds_read_b128 v[164:167], v239 offset:21504
	ds_read_b128 v[168:171], v239 offset:22528
	ds_read_b128 v[172:175], v239 offset:23552
	global_load_lds_dwordx4 v[212:213], off
	v_lshl_add_u64 v[214:215], s[40:41], 0, v[188:189]
	s_mov_b32 m0, s4
	s_nop 0
	global_load_lds_dwordx4 v[214:215], off
	s_barrier
	s_waitcnt lgkmcnt(0)
	s_waitcnt lgkmcnt(0)
	v_mfma_f32_16x16x32_bf16 v[60:63], v[128:131], v[144:147], 0
	v_mfma_f32_16x16x32_bf16 v[52:55], v[136:139], v[144:147], 0
	v_mfma_f32_16x16x32_bf16 v[44:47], v[128:131], v[152:155], 0
	v_mfma_f32_16x16x32_bf16 v[36:39], v[136:139], v[152:155], 0
	v_mfma_f32_16x16x32_bf16 v[28:31], v[128:131], v[160:163], 0
	v_mfma_f32_16x16x32_bf16 v[20:23], v[136:139], v[160:163], 0
	v_mfma_f32_16x16x32_bf16 v[12:15], v[128:131], v[168:171], 0
	v_mfma_f32_16x16x32_bf16 v[4:7], v[136:139], v[168:171], 0
	v_mfma_f32_16x16x32_bf16 v[60:63], v[132:135], v[148:151], v[60:63]
	v_mfma_f32_16x16x32_bf16 v[52:55], v[140:143], v[148:151], v[52:55]
	v_mfma_f32_16x16x32_bf16 v[44:47], v[132:135], v[156:159], v[44:47]
	v_mfma_f32_16x16x32_bf16 v[36:39], v[140:143], v[156:159], v[36:39]
	v_mfma_f32_16x16x32_bf16 v[28:31], v[132:135], v[164:167], v[28:31]
	v_mfma_f32_16x16x32_bf16 v[20:23], v[140:143], v[164:167], v[20:23]
	v_mfma_f32_16x16x32_bf16 v[12:15], v[132:135], v[172:175], v[12:15]
	v_mfma_f32_16x16x32_bf16 v[4:7], v[140:143], v[172:175], v[4:7]
	s_barrier
	s_add_u32 s68, s68, s98
	s_addc_u32 s69, s69, 0
	s_add_i32 s73, s80, s33
	v_lshl_add_u64 v[216:217], s[68:69], 0, v[186:187]
	s_mov_b32 m0, s73
	v_lshl_add_u64 v[218:219], s[68:69], 0, v[190:191]
	global_load_lds_dwordx4 v[216:217], off
	s_add_i32 m0, s73, 0x2000
	s_nop 0
	global_load_lds_dwordx4 v[218:219], off
	s_waitcnt vmcnt(6)
	s_barrier
	v_mfma_f32_16x16x32_bf16 v[56:59], v[176:179], v[144:147], 0
	v_mfma_f32_16x16x32_bf16 v[48:51], v[200:203], v[144:147], 0
	v_mfma_f32_16x16x32_bf16 v[40:43], v[176:179], v[152:155], 0
	v_mfma_f32_16x16x32_bf16 v[32:35], v[200:203], v[152:155], 0
	v_mfma_f32_16x16x32_bf16 v[24:27], v[176:179], v[160:163], 0
	v_mfma_f32_16x16x32_bf16 v[16:19], v[200:203], v[160:163], 0
	v_mfma_f32_16x16x32_bf16 v[8:11], v[176:179], v[168:171], 0
	v_mfma_f32_16x16x32_bf16 v[0:3], v[200:203], v[168:171], 0
	v_mfma_f32_16x16x32_bf16 v[56:59], v[196:199], v[148:151], v[56:59]
	v_mfma_f32_16x16x32_bf16 v[48:51], v[204:207], v[148:151], v[48:51]
	v_mfma_f32_16x16x32_bf16 v[40:43], v[196:199], v[156:159], v[40:43]
	v_mfma_f32_16x16x32_bf16 v[32:35], v[204:207], v[156:159], v[32:35]
	v_mfma_f32_16x16x32_bf16 v[24:27], v[196:199], v[164:167], v[24:27]
	v_mfma_f32_16x16x32_bf16 v[16:19], v[204:207], v[164:167], v[16:19]
	v_mfma_f32_16x16x32_bf16 v[8:11], v[196:199], v[172:175], v[8:11]
	v_mfma_f32_16x16x32_bf16 v[0:3], v[204:207], v[172:175], v[0:3]
	s_add_i32 s68, 0, 0x18000
	v_add_u32_e32 v140, s68, v183
	s_barrier
	ds_read_b128 v[128:131], v140
	ds_read_b128 v[132:135], v140 offset:1024
	ds_read_b128 v[136:139], v140 offset:2048
	ds_read_b128 v[140:143], v140 offset:3072
	s_add_u32 s40, s40, s98
	s_addc_u32 s41, s41, 0
	s_mov_b32 m0, s5
	v_lshl_add_u64 v[176:177], s[40:41], 0, v[184:185]
	ds_read_b128 v[144:147], v239 offset:32768
	ds_read_b128 v[148:151], v239 offset:33792
	ds_read_b128 v[152:155], v239 offset:34816
	ds_read_b128 v[156:159], v239 offset:35840
	ds_read_b128 v[160:163], v239 offset:36864
	ds_read_b128 v[164:167], v239 offset:37888
	ds_read_b128 v[168:171], v239 offset:38912
	ds_read_b128 v[172:175], v239 offset:39936
	global_load_lds_dwordx4 v[176:177], off
	v_lshl_add_u64 v[176:177], s[40:41], 0, v[188:189]
	s_mov_b32 m0, s6
	s_nop 0
	global_load_lds_dwordx4 v[176:177], off
	s_waitcnt lgkmcnt(8)
	s_barrier
	s_waitcnt lgkmcnt(0)
	s_waitcnt lgkmcnt(0)
	v_mfma_f32_16x16x32_bf16 v[124:127], v[128:131], v[144:147], v[124:127]
	v_mfma_f32_16x16x32_bf16 v[116:119], v[136:139], v[144:147], v[116:119]
	v_mfma_f32_16x16x32_bf16 v[108:111], v[128:131], v[152:155], v[108:111]
	v_mfma_f32_16x16x32_bf16 v[100:103], v[136:139], v[152:155], v[100:103]
	v_mfma_f32_16x16x32_bf16 v[92:95], v[128:131], v[160:163], v[92:95]
	v_mfma_f32_16x16x32_bf16 v[84:87], v[136:139], v[160:163], v[84:87]
	v_mfma_f32_16x16x32_bf16 v[76:79], v[128:131], v[168:171], v[76:79]
	v_mfma_f32_16x16x32_bf16 v[68:71], v[136:139], v[168:171], v[68:71]
	v_mfma_f32_16x16x32_bf16 v[124:127], v[132:135], v[148:151], v[124:127]
	v_mfma_f32_16x16x32_bf16 v[116:119], v[140:143], v[148:151], v[116:119]
	v_mfma_f32_16x16x32_bf16 v[108:111], v[132:135], v[156:159], v[108:111]
	v_mfma_f32_16x16x32_bf16 v[100:103], v[140:143], v[156:159], v[100:103]
	v_mfma_f32_16x16x32_bf16 v[92:95], v[132:135], v[164:167], v[92:95]
	v_mfma_f32_16x16x32_bf16 v[84:87], v[140:143], v[164:167], v[84:87]
	v_mfma_f32_16x16x32_bf16 v[76:79], v[132:135], v[172:175], v[76:79]
	v_mfma_f32_16x16x32_bf16 v[68:71], v[140:143], v[172:175], v[68:71]
	s_barrier
	s_add_i32 s40, 0, 0x1c000
	s_add_i32 s41, s68, s33
	v_add_u32_e32 v204, s40, v183
	v_lshl_add_u64 v[208:209], v[208:209], 0, s[96:97]
	s_mov_b32 m0, s41
	ds_read_b128 v[176:179], v204
	ds_read_b128 v[196:199], v204 offset:1024
	ds_read_b128 v[200:203], v204 offset:2048
	ds_read_b128 v[204:207], v204 offset:3072
	global_load_lds_dwordx4 v[208:209], off
	v_lshl_add_u64 v[208:209], v[210:211], 0, s[96:97]
	s_add_i32 m0, s41, 0x2000
	s_nop 0
	global_load_lds_dwordx4 v[208:209], off
	s_barrier
	s_waitcnt lgkmcnt(0)
	s_waitcnt lgkmcnt(0)
	v_mfma_f32_16x16x32_bf16 v[120:123], v[176:179], v[144:147], v[120:123]
	v_mfma_f32_16x16x32_bf16 v[112:115], v[200:203], v[144:147], v[112:115]
	v_mfma_f32_16x16x32_bf16 v[104:107], v[176:179], v[152:155], v[104:107]
	v_mfma_f32_16x16x32_bf16 v[96:99], v[200:203], v[152:155], v[96:99]
	v_mfma_f32_16x16x32_bf16 v[88:91], v[176:179], v[160:163], v[88:91]
	v_mfma_f32_16x16x32_bf16 v[80:83], v[200:203], v[160:163], v[80:83]
	v_mfma_f32_16x16x32_bf16 v[72:75], v[176:179], v[168:171], v[72:75]
	v_mfma_f32_16x16x32_bf16 v[64:67], v[200:203], v[168:171], v[64:67]
	v_mfma_f32_16x16x32_bf16 v[120:123], v[196:199], v[148:151], v[120:123]
	v_mfma_f32_16x16x32_bf16 v[112:115], v[204:207], v[148:151], v[112:115]
	v_mfma_f32_16x16x32_bf16 v[104:107], v[196:199], v[156:159], v[104:107]
	v_mfma_f32_16x16x32_bf16 v[96:99], v[204:207], v[156:159], v[96:99]
	v_mfma_f32_16x16x32_bf16 v[88:91], v[196:199], v[164:167], v[88:91]
	v_mfma_f32_16x16x32_bf16 v[80:83], v[204:207], v[164:167], v[80:83]
	v_mfma_f32_16x16x32_bf16 v[72:75], v[196:199], v[172:175], v[72:75]
	v_mfma_f32_16x16x32_bf16 v[64:67], v[204:207], v[172:175], v[64:67]
	s_mov_b32 m0, s8
	v_lshl_add_u64 v[208:209], v[212:213], 0, s[96:97]
	s_barrier
	ds_read_b128 v[144:147], v239 offset:49152
	ds_read_b128 v[148:151], v239 offset:50176
	ds_read_b128 v[152:155], v239 offset:51200
	ds_read_b128 v[156:159], v239 offset:52224
	ds_read_b128 v[160:163], v239 offset:53248
	ds_read_b128 v[164:167], v239 offset:54272
	ds_read_b128 v[168:171], v239 offset:55296
	ds_read_b128 v[172:175], v239 offset:56320
	global_load_lds_dwordx4 v[208:209], off
	v_lshl_add_u64 v[208:209], v[214:215], 0, s[96:97]
	s_mov_b32 m0, s9
	s_nop 0
	global_load_lds_dwordx4 v[208:209], off
	s_barrier
	s_waitcnt lgkmcnt(0)
	s_waitcnt lgkmcnt(0)
	v_mfma_f32_16x16x32_bf16 v[60:63], v[128:131], v[144:147], v[60:63]
	v_mfma_f32_16x16x32_bf16 v[52:55], v[136:139], v[144:147], v[52:55]
	v_mfma_f32_16x16x32_bf16 v[44:47], v[128:131], v[152:155], v[44:47]
	v_mfma_f32_16x16x32_bf16 v[36:39], v[136:139], v[152:155], v[36:39]
	v_mfma_f32_16x16x32_bf16 v[28:31], v[128:131], v[160:163], v[28:31]
	v_mfma_f32_16x16x32_bf16 v[20:23], v[136:139], v[160:163], v[20:23]
	v_mfma_f32_16x16x32_bf16 v[12:15], v[128:131], v[168:171], v[12:15]
	v_mfma_f32_16x16x32_bf16 v[4:7], v[136:139], v[168:171], v[4:7]
	v_mfma_f32_16x16x32_bf16 v[60:63], v[132:135], v[148:151], v[60:63]
	v_mfma_f32_16x16x32_bf16 v[52:55], v[140:143], v[148:151], v[52:55]
	v_mfma_f32_16x16x32_bf16 v[44:47], v[132:135], v[156:159], v[44:47]
	v_mfma_f32_16x16x32_bf16 v[36:39], v[140:143], v[156:159], v[36:39]
	v_mfma_f32_16x16x32_bf16 v[28:31], v[132:135], v[164:167], v[28:31]
	v_mfma_f32_16x16x32_bf16 v[20:23], v[140:143], v[164:167], v[20:23]
	v_mfma_f32_16x16x32_bf16 v[12:15], v[132:135], v[172:175], v[12:15]
	v_mfma_f32_16x16x32_bf16 v[4:7], v[140:143], v[172:175], v[4:7]
	s_barrier
	s_add_i32 s40, s40, s33
	v_lshl_add_u64 v[128:129], v[216:217], 0, s[96:97]
	s_mov_b32 m0, s40
	s_nop 0
	global_load_lds_dwordx4 v[128:129], off
	v_lshl_add_u64 v[128:129], v[218:219], 0, s[96:97]
	s_add_i32 m0, s40, 0x2000
	s_nop 0
	global_load_lds_dwordx4 v[128:129], off
	s_waitcnt vmcnt(6)
	s_barrier
	v_mfma_f32_16x16x32_bf16 v[56:59], v[176:179], v[144:147], v[56:59]
	v_mfma_f32_16x16x32_bf16 v[48:51], v[200:203], v[144:147], v[48:51]
	v_mfma_f32_16x16x32_bf16 v[40:43], v[176:179], v[152:155], v[40:43]
	v_mfma_f32_16x16x32_bf16 v[32:35], v[200:203], v[152:155], v[32:35]
	v_mfma_f32_16x16x32_bf16 v[24:27], v[176:179], v[160:163], v[24:27]
	v_mfma_f32_16x16x32_bf16 v[16:19], v[200:203], v[160:163], v[16:19]
	v_mfma_f32_16x16x32_bf16 v[8:11], v[176:179], v[168:171], v[8:11]
	v_mfma_f32_16x16x32_bf16 v[0:3], v[200:203], v[168:171], v[0:3]
	v_mfma_f32_16x16x32_bf16 v[56:59], v[196:199], v[148:151], v[56:59]
	v_mfma_f32_16x16x32_bf16 v[48:51], v[204:207], v[148:151], v[48:51]
	v_mfma_f32_16x16x32_bf16 v[40:43], v[196:199], v[156:159], v[40:43]
	v_mfma_f32_16x16x32_bf16 v[32:35], v[204:207], v[156:159], v[32:35]
	v_mfma_f32_16x16x32_bf16 v[24:27], v[196:199], v[164:167], v[24:27]
	v_mfma_f32_16x16x32_bf16 v[16:19], v[204:207], v[164:167], v[16:19]
	v_mfma_f32_16x16x32_bf16 v[8:11], v[196:199], v[172:175], v[8:11]
	v_mfma_f32_16x16x32_bf16 v[0:3], v[204:207], v[172:175], v[0:3]
	s_add_u32 s0, s0, 0x100
	s_addc_u32 s1, s1, 0
	s_add_u32 s70, s70, 0x100
	s_addc_u32 s71, s71, 0
	s_cmp_ge_u32 s72, s7
	s_mov_b32 s40, s72
	s_barrier
	s_cbranch_scc0 .LBB0_141
	s_branch .Lgemm_kloop_done

.Lgemm_kloop_done:
	v_lshl_add_u32 v196, s19, 8, v181
	s_cmp_lt_i32 s78, 2
	s_mov_b64 s[0:1], -1
	s_cbranch_scc1 .LBB0_223
	s_cmp_gt_i32 s78, 2
	s_cbranch_scc0 .LBB0_220
	s_lshl_b32 s0, s18, 8
	s_ashr_i32 s68, s18, 1
	s_nop 0
	s_and_b32 s0, s0, 0x100
	v_or_b32_e64 v147, s0, v238
	s_lshl_b32 s72, s68, 25
	s_nop 0
	v_lshl_add_u32 v146, v196, 9, v147
	v_lshlrev_b32_e64 v146, 1, v146
	v_add_u32_e64 v146, s72, v146
	s_cmp_gt_i32 s68, 3
	s_cbranch_scc1 .Lepi3_plain
	v_readlane_b32 s40, v241, 10
	v_readlane_b32 s41, v241, 11
	v_readlane_b32 s70, v241, 14
	v_readlane_b32 s71, v241, 15
	v_lshlrev_b32_e64 v147, 2, v147
	v_mov_b32_e32 v144, 0xbfb8aa3b
	s_lshl_b32 s69, s68, 11
	s_nop 3
	s_cmp_lt_i32 s68, 2
	s_cselect_b64 s[0:1], -1, 0
	s_cselect_b32 s40, s40, s70
	s_cselect_b32 s41, s41, s71
	s_cselect_b32 s72, 0, 0x1000
	s_sub_u32 s69, s69, s72
	s_add_u32 s40, s40, s69
	s_addc_u32 s41, s41, 0
	s_nop 0
	v_cndmask_b32_e64 v158, 1.0, v235, s[0:1]
	global_load_dwordx4 v[128:131], v147, s[40:41]
	global_load_dwordx4 v[132:135], v147, s[40:41] offset:16
	global_load_dwordx4 v[136:139], v147, s[40:41] offset:512
	global_load_dwordx4 v[140:143], v147, s[40:41] offset:528
	s_waitcnt vmcnt(0)
	s_nop 0
	v_pk_add_f32 v[124:125], v[124:125], v[128:129]
	v_pk_add_f32 v[126:127], v[126:127], v[130:131]
	v_pk_add_f32 v[116:117], v[116:117], v[132:133]
	v_pk_add_f32 v[118:119], v[118:119], v[134:135]
	v_pk_mul_f32 v[124:125], v[124:125], v[144:145] op_sel_hi:[1,0]
	v_pk_mul_f32 v[126:127], v[126:127], v[144:145] op_sel_hi:[1,0]
	v_pk_mul_f32 v[116:117], v[116:117], v[144:145] op_sel_hi:[1,0]
	v_pk_mul_f32 v[118:119], v[118:119], v[144:145] op_sel_hi:[1,0]
	v_exp_f32_e64 v124, v124
	v_exp_f32_e64 v125, v125
	v_exp_f32_e64 v126, v126
	v_exp_f32_e64 v127, v127
	v_exp_f32_e64 v116, v116
	v_exp_f32_e64 v117, v117
	v_exp_f32_e64 v118, v118
	v_exp_f32_e64 v119, v119
	v_pk_add_f32 v[124:125], v[124:125], 1.0 op_sel_hi:[1,0]
	v_pk_add_f32 v[126:127], v[126:127], 1.0 op_sel_hi:[1,0]
	v_pk_add_f32 v[116:117], v[116:117], 1.0 op_sel_hi:[1,0]
	v_pk_add_f32 v[118:119], v[118:119], 1.0 op_sel_hi:[1,0]
	v_rcp_f32_e64 v124, v124
	v_rcp_f32_e64 v125, v125
	v_rcp_f32_e64 v126, v126
	v_rcp_f32_e64 v127, v127
	v_rcp_f32_e64 v116, v116
	v_rcp_f32_e64 v117, v117
	v_rcp_f32_e64 v118, v118
	v_rcp_f32_e64 v119, v119
	v_pk_mul_f32 v[124:125], v[124:125], v[158:159] op_sel_hi:[1,0]
	v_pk_mul_f32 v[126:127], v[126:127], v[158:159] op_sel_hi:[1,0]
	v_pk_mul_f32 v[116:117], v[116:117], v[158:159] op_sel_hi:[1,0]
	v_pk_mul_f32 v[118:119], v[118:119], v[158:159] op_sel_hi:[1,0]
	v_cvt_pk_f16_f32 v148, v124, v125
	v_cvt_pk_f16_f32 v149, v126, v127
	v_cvt_pk_f16_f32 v150, v116, v117
	v_cvt_pk_f16_f32 v151, v118, v119
	global_store_dwordx4 v146, v[148:151], s[86:87]
	v_pk_add_f32 v[120:121], v[120:121], v[136:137]
	v_pk_add_f32 v[122:123], v[122:123], v[138:139]
	v_pk_add_f32 v[112:113], v[112:113], v[140:141]
	v_pk_add_f32 v[114:115], v[114:115], v[142:143]
	v_pk_mul_f32 v[120:121], v[120:121], v[144:145] op_sel_hi:[1,0]
	v_pk_mul_f32 v[122:123], v[122:123], v[144:145] op_sel_hi:[1,0]
	v_pk_mul_f32 v[112:113], v[112:113], v[144:145] op_sel_hi:[1,0]
	v_pk_mul_f32 v[114:115], v[114:115], v[144:145] op_sel_hi:[1,0]
	v_exp_f32_e64 v120, v120
	v_exp_f32_e64 v121, v121
	v_exp_f32_e64 v122, v122
	v_exp_f32_e64 v123, v123
	v_exp_f32_e64 v112, v112
	v_exp_f32_e64 v113, v113
	v_exp_f32_e64 v114, v114
	v_exp_f32_e64 v115, v115
	v_pk_add_f32 v[120:121], v[120:121], 1.0 op_sel_hi:[1,0]
	v_pk_add_f32 v[122:123], v[122:123], 1.0 op_sel_hi:[1,0]
	v_pk_add_f32 v[112:113], v[112:113], 1.0 op_sel_hi:[1,0]
	v_pk_add_f32 v[114:115], v[114:115], 1.0 op_sel_hi:[1,0]
	v_rcp_f32_e64 v120, v120
	v_rcp_f32_e64 v121, v121
	v_rcp_f32_e64 v122, v122
	v_rcp_f32_e64 v123, v123
	v_rcp_f32_e64 v112, v112
	v_rcp_f32_e64 v113, v113
	v_rcp_f32_e64 v114, v114
	v_rcp_f32_e64 v115, v115
	v_pk_mul_f32 v[120:121], v[120:121], v[158:159] op_sel_hi:[1,0]
	v_pk_mul_f32 v[122:123], v[122:123], v[158:159] op_sel_hi:[1,0]
	v_pk_mul_f32 v[112:113], v[112:113], v[158:159] op_sel_hi:[1,0]
	v_pk_mul_f32 v[114:115], v[114:115], v[158:159] op_sel_hi:[1,0]
	v_cvt_pk_f16_f32 v152, v120, v121
	v_cvt_pk_f16_f32 v153, v122, v123
	v_cvt_pk_f16_f32 v154, v112, v113
	v_cvt_pk_f16_f32 v155, v114, v115
	global_store_dwordx4 v146, v[152:155], s[86:87] offset:256
	v_add_u32_e32 v146, 0x4000, v146
	v_pk_add_f32 v[108:109], v[108:109], v[128:129]
	v_pk_add_f32 v[110:111], v[110:111], v[130:131]
	v_pk_add_f32 v[100:101], v[100:101], v[132:133]
	v_pk_add_f32 v[102:103], v[102:103], v[134:135]
	v_pk_mul_f32 v[108:109], v[108:109], v[144:145] op_sel_hi:[1,0]
	v_pk_mul_f32 v[110:111], v[110:111], v[144:145] op_sel_hi:[1,0]
	v_pk_mul_f32 v[100:101], v[100:101], v[144:145] op_sel_hi:[1,0]
	v_pk_mul_f32 v[102:103], v[102:103], v[144:145] op_sel_hi:[1,0]
	v_exp_f32_e64 v108, v108
	v_exp_f32_e64 v109, v109
	v_exp_f32_e64 v110, v110
	v_exp_f32_e64 v111, v111
	v_exp_f32_e64 v100, v100
	v_exp_f32_e64 v101, v101
	v_exp_f32_e64 v102, v102
	v_exp_f32_e64 v103, v103
	v_pk_add_f32 v[108:109], v[108:109], 1.0 op_sel_hi:[1,0]
	v_pk_add_f32 v[110:111], v[110:111], 1.0 op_sel_hi:[1,0]
	v_pk_add_f32 v[100:101], v[100:101], 1.0 op_sel_hi:[1,0]
	v_pk_add_f32 v[102:103], v[102:103], 1.0 op_sel_hi:[1,0]
	v_rcp_f32_e64 v108, v108
	v_rcp_f32_e64 v109, v109
	v_rcp_f32_e64 v110, v110
	v_rcp_f32_e64 v111, v111
	v_rcp_f32_e64 v100, v100
	v_rcp_f32_e64 v101, v101
	v_rcp_f32_e64 v102, v102
	v_rcp_f32_e64 v103, v103
	v_pk_mul_f32 v[108:109], v[108:109], v[158:159] op_sel_hi:[1,0]
	v_pk_mul_f32 v[110:111], v[110:111], v[158:159] op_sel_hi:[1,0]
	v_pk_mul_f32 v[100:101], v[100:101], v[158:159] op_sel_hi:[1,0]
	v_pk_mul_f32 v[102:103], v[102:103], v[158:159] op_sel_hi:[1,0]
	v_cvt_pk_f16_f32 v148, v108, v109
	v_cvt_pk_f16_f32 v149, v110, v111
	v_cvt_pk_f16_f32 v150, v100, v101
	v_cvt_pk_f16_f32 v151, v102, v103
	global_store_dwordx4 v146, v[148:151], s[86:87]
	v_pk_add_f32 v[104:105], v[104:105], v[136:137]
	v_pk_add_f32 v[106:107], v[106:107], v[138:139]
	v_pk_add_f32 v[96:97], v[96:97], v[140:141]
	v_pk_add_f32 v[98:99], v[98:99], v[142:143]
	v_pk_mul_f32 v[104:105], v[104:105], v[144:145] op_sel_hi:[1,0]
	v_pk_mul_f32 v[106:107], v[106:107], v[144:145] op_sel_hi:[1,0]
	v_pk_mul_f32 v[96:97], v[96:97], v[144:145] op_sel_hi:[1,0]
	v_pk_mul_f32 v[98:99], v[98:99], v[144:145] op_sel_hi:[1,0]
	v_exp_f32_e64 v104, v104
	v_exp_f32_e64 v105, v105
	v_exp_f32_e64 v106, v106
	v_exp_f32_e64 v107, v107
	v_exp_f32_e64 v96, v96
	v_exp_f32_e64 v97, v97
	v_exp_f32_e64 v98, v98
	v_exp_f32_e64 v99, v99
	v_pk_add_f32 v[104:105], v[104:105], 1.0 op_sel_hi:[1,0]
	v_pk_add_f32 v[106:107], v[106:107], 1.0 op_sel_hi:[1,0]
	v_pk_add_f32 v[96:97], v[96:97], 1.0 op_sel_hi:[1,0]
	v_pk_add_f32 v[98:99], v[98:99], 1.0 op_sel_hi:[1,0]
	v_rcp_f32_e64 v104, v104
	v_rcp_f32_e64 v105, v105
	v_rcp_f32_e64 v106, v106
	v_rcp_f32_e64 v107, v107
	v_rcp_f32_e64 v96, v96
	v_rcp_f32_e64 v97, v97
	v_rcp_f32_e64 v98, v98
	v_rcp_f32_e64 v99, v99
	v_pk_mul_f32 v[104:105], v[104:105], v[158:159] op_sel_hi:[1,0]
	v_pk_mul_f32 v[106:107], v[106:107], v[158:159] op_sel_hi:[1,0]
	v_pk_mul_f32 v[96:97], v[96:97], v[158:159] op_sel_hi:[1,0]
	v_pk_mul_f32 v[98:99], v[98:99], v[158:159] op_sel_hi:[1,0]
	v_cvt_pk_f16_f32 v152, v104, v105
	v_cvt_pk_f16_f32 v153, v106, v107
	v_cvt_pk_f16_f32 v154, v96, v97
	v_cvt_pk_f16_f32 v155, v98, v99
	global_store_dwordx4 v146, v[152:155], s[86:87] offset:256
	v_add_u32_e32 v146, 0x4000, v146
	v_pk_add_f32 v[92:93], v[92:93], v[128:129]
	v_pk_add_f32 v[94:95], v[94:95], v[130:131]
	v_pk_add_f32 v[84:85], v[84:85], v[132:133]
	v_pk_add_f32 v[86:87], v[86:87], v[134:135]
	v_pk_mul_f32 v[92:93], v[92:93], v[144:145] op_sel_hi:[1,0]
	v_pk_mul_f32 v[94:95], v[94:95], v[144:145] op_sel_hi:[1,0]
	v_pk_mul_f32 v[84:85], v[84:85], v[144:145] op_sel_hi:[1,0]
	v_pk_mul_f32 v[86:87], v[86:87], v[144:145] op_sel_hi:[1,0]
	v_exp_f32_e64 v92, v92
	v_exp_f32_e64 v93, v93
	v_exp_f32_e64 v94, v94
	v_exp_f32_e64 v95, v95
	v_exp_f32_e64 v84, v84
	v_exp_f32_e64 v85, v85
	v_exp_f32_e64 v86, v86
	v_exp_f32_e64 v87, v87
	v_pk_add_f32 v[92:93], v[92:93], 1.0 op_sel_hi:[1,0]
	v_pk_add_f32 v[94:95], v[94:95], 1.0 op_sel_hi:[1,0]
	v_pk_add_f32 v[84:85], v[84:85], 1.0 op_sel_hi:[1,0]
	v_pk_add_f32 v[86:87], v[86:87], 1.0 op_sel_hi:[1,0]
	v_rcp_f32_e64 v92, v92
	v_rcp_f32_e64 v93, v93
	v_rcp_f32_e64 v94, v94
	v_rcp_f32_e64 v95, v95
	v_rcp_f32_e64 v84, v84
	v_rcp_f32_e64 v85, v85
	v_rcp_f32_e64 v86, v86
	v_rcp_f32_e64 v87, v87
	v_pk_mul_f32 v[92:93], v[92:93], v[158:159] op_sel_hi:[1,0]
	v_pk_mul_f32 v[94:95], v[94:95], v[158:159] op_sel_hi:[1,0]
	v_pk_mul_f32 v[84:85], v[84:85], v[158:159] op_sel_hi:[1,0]
	v_pk_mul_f32 v[86:87], v[86:87], v[158:159] op_sel_hi:[1,0]
	v_cvt_pk_f16_f32 v148, v92, v93
	v_cvt_pk_f16_f32 v149, v94, v95
	v_cvt_pk_f16_f32 v150, v84, v85
	v_cvt_pk_f16_f32 v151, v86, v87
	global_store_dwordx4 v146, v[148:151], s[86:87]
	v_pk_add_f32 v[88:89], v[88:89], v[136:137]
	v_pk_add_f32 v[90:91], v[90:91], v[138:139]
	v_pk_add_f32 v[80:81], v[80:81], v[140:141]
	v_pk_add_f32 v[82:83], v[82:83], v[142:143]
	v_pk_mul_f32 v[88:89], v[88:89], v[144:145] op_sel_hi:[1,0]
	v_pk_mul_f32 v[90:91], v[90:91], v[144:145] op_sel_hi:[1,0]
	v_pk_mul_f32 v[80:81], v[80:81], v[144:145] op_sel_hi:[1,0]
	v_pk_mul_f32 v[82:83], v[82:83], v[144:145] op_sel_hi:[1,0]
	v_exp_f32_e64 v88, v88
	v_exp_f32_e64 v89, v89
	v_exp_f32_e64 v90, v90
	v_exp_f32_e64 v91, v91
	v_exp_f32_e64 v80, v80
	v_exp_f32_e64 v81, v81
	v_exp_f32_e64 v82, v82
	v_exp_f32_e64 v83, v83
	v_pk_add_f32 v[88:89], v[88:89], 1.0 op_sel_hi:[1,0]
	v_pk_add_f32 v[90:91], v[90:91], 1.0 op_sel_hi:[1,0]
	v_pk_add_f32 v[80:81], v[80:81], 1.0 op_sel_hi:[1,0]
	v_pk_add_f32 v[82:83], v[82:83], 1.0 op_sel_hi:[1,0]
	v_rcp_f32_e64 v88, v88
	v_rcp_f32_e64 v89, v89
	v_rcp_f32_e64 v90, v90
	v_rcp_f32_e64 v91, v91
	v_rcp_f32_e64 v80, v80
	v_rcp_f32_e64 v81, v81
	v_rcp_f32_e64 v82, v82
	v_rcp_f32_e64 v83, v83
	v_pk_mul_f32 v[88:89], v[88:89], v[158:159] op_sel_hi:[1,0]
	v_pk_mul_f32 v[90:91], v[90:91], v[158:159] op_sel_hi:[1,0]
	v_pk_mul_f32 v[80:81], v[80:81], v[158:159] op_sel_hi:[1,0]
	v_pk_mul_f32 v[82:83], v[82:83], v[158:159] op_sel_hi:[1,0]
	v_cvt_pk_f16_f32 v152, v88, v89
	v_cvt_pk_f16_f32 v153, v90, v91
	v_cvt_pk_f16_f32 v154, v80, v81
	v_cvt_pk_f16_f32 v155, v82, v83
	global_store_dwordx4 v146, v[152:155], s[86:87] offset:256
	v_add_u32_e32 v146, 0x4000, v146
	v_pk_add_f32 v[76:77], v[76:77], v[128:129]
	v_pk_add_f32 v[78:79], v[78:79], v[130:131]
	v_pk_add_f32 v[68:69], v[68:69], v[132:133]
	v_pk_add_f32 v[70:71], v[70:71], v[134:135]
	v_pk_mul_f32 v[76:77], v[76:77], v[144:145] op_sel_hi:[1,0]
	v_pk_mul_f32 v[78:79], v[78:79], v[144:145] op_sel_hi:[1,0]
	v_pk_mul_f32 v[68:69], v[68:69], v[144:145] op_sel_hi:[1,0]
	v_pk_mul_f32 v[70:71], v[70:71], v[144:145] op_sel_hi:[1,0]
	v_exp_f32_e64 v76, v76
	v_exp_f32_e64 v77, v77
	v_exp_f32_e64 v78, v78
	v_exp_f32_e64 v79, v79
	v_exp_f32_e64 v68, v68
	v_exp_f32_e64 v69, v69
	v_exp_f32_e64 v70, v70
	v_exp_f32_e64 v71, v71
	v_pk_add_f32 v[76:77], v[76:77], 1.0 op_sel_hi:[1,0]
	v_pk_add_f32 v[78:79], v[78:79], 1.0 op_sel_hi:[1,0]
	v_pk_add_f32 v[68:69], v[68:69], 1.0 op_sel_hi:[1,0]
	v_pk_add_f32 v[70:71], v[70:71], 1.0 op_sel_hi:[1,0]
	v_rcp_f32_e64 v76, v76
	v_rcp_f32_e64 v77, v77
	v_rcp_f32_e64 v78, v78
	v_rcp_f32_e64 v79, v79
	v_rcp_f32_e64 v68, v68
	v_rcp_f32_e64 v69, v69
	v_rcp_f32_e64 v70, v70
	v_rcp_f32_e64 v71, v71
	v_pk_mul_f32 v[76:77], v[76:77], v[158:159] op_sel_hi:[1,0]
	v_pk_mul_f32 v[78:79], v[78:79], v[158:159] op_sel_hi:[1,0]
	v_pk_mul_f32 v[68:69], v[68:69], v[158:159] op_sel_hi:[1,0]
	v_pk_mul_f32 v[70:71], v[70:71], v[158:159] op_sel_hi:[1,0]
	v_cvt_pk_f16_f32 v148, v76, v77
	v_cvt_pk_f16_f32 v149, v78, v79
	v_cvt_pk_f16_f32 v150, v68, v69
	v_cvt_pk_f16_f32 v151, v70, v71
	global_store_dwordx4 v146, v[148:151], s[86:87]
	v_pk_add_f32 v[72:73], v[72:73], v[136:137]
	v_pk_add_f32 v[74:75], v[74:75], v[138:139]
	v_pk_add_f32 v[64:65], v[64:65], v[140:141]
	v_pk_add_f32 v[66:67], v[66:67], v[142:143]
	v_pk_mul_f32 v[72:73], v[72:73], v[144:145] op_sel_hi:[1,0]
	v_pk_mul_f32 v[74:75], v[74:75], v[144:145] op_sel_hi:[1,0]
	v_pk_mul_f32 v[64:65], v[64:65], v[144:145] op_sel_hi:[1,0]
	v_pk_mul_f32 v[66:67], v[66:67], v[144:145] op_sel_hi:[1,0]
	v_exp_f32_e64 v72, v72
	v_exp_f32_e64 v73, v73
	v_exp_f32_e64 v74, v74
	v_exp_f32_e64 v75, v75
	v_exp_f32_e64 v64, v64
	v_exp_f32_e64 v65, v65
	v_exp_f32_e64 v66, v66
	v_exp_f32_e64 v67, v67
	v_pk_add_f32 v[72:73], v[72:73], 1.0 op_sel_hi:[1,0]
	v_pk_add_f32 v[74:75], v[74:75], 1.0 op_sel_hi:[1,0]
	v_pk_add_f32 v[64:65], v[64:65], 1.0 op_sel_hi:[1,0]
	v_pk_add_f32 v[66:67], v[66:67], 1.0 op_sel_hi:[1,0]
	v_rcp_f32_e64 v72, v72
	v_rcp_f32_e64 v73, v73
	v_rcp_f32_e64 v74, v74
	v_rcp_f32_e64 v75, v75
	v_rcp_f32_e64 v64, v64
	v_rcp_f32_e64 v65, v65
	v_rcp_f32_e64 v66, v66
	v_rcp_f32_e64 v67, v67
	v_pk_mul_f32 v[72:73], v[72:73], v[158:159] op_sel_hi:[1,0]
	v_pk_mul_f32 v[74:75], v[74:75], v[158:159] op_sel_hi:[1,0]
	v_pk_mul_f32 v[64:65], v[64:65], v[158:159] op_sel_hi:[1,0]
	v_pk_mul_f32 v[66:67], v[66:67], v[158:159] op_sel_hi:[1,0]
	v_cvt_pk_f16_f32 v152, v72, v73
	v_cvt_pk_f16_f32 v153, v74, v75
	v_cvt_pk_f16_f32 v154, v64, v65
	v_cvt_pk_f16_f32 v155, v66, v67
	global_store_dwordx4 v146, v[152:155], s[86:87] offset:256
	v_add_u32_e32 v146, 0x14000, v146
	v_pk_add_f32 v[60:61], v[60:61], v[128:129]
	v_pk_add_f32 v[62:63], v[62:63], v[130:131]
	v_pk_add_f32 v[52:53], v[52:53], v[132:133]
	v_pk_add_f32 v[54:55], v[54:55], v[134:135]
	v_pk_mul_f32 v[60:61], v[60:61], v[144:145] op_sel_hi:[1,0]
	v_pk_mul_f32 v[62:63], v[62:63], v[144:145] op_sel_hi:[1,0]
	v_pk_mul_f32 v[52:53], v[52:53], v[144:145] op_sel_hi:[1,0]
	v_pk_mul_f32 v[54:55], v[54:55], v[144:145] op_sel_hi:[1,0]
	v_exp_f32_e64 v60, v60
	v_exp_f32_e64 v61, v61
	v_exp_f32_e64 v62, v62
	v_exp_f32_e64 v63, v63
	v_exp_f32_e64 v52, v52
	v_exp_f32_e64 v53, v53
	v_exp_f32_e64 v54, v54
	v_exp_f32_e64 v55, v55
	v_pk_add_f32 v[60:61], v[60:61], 1.0 op_sel_hi:[1,0]
	v_pk_add_f32 v[62:63], v[62:63], 1.0 op_sel_hi:[1,0]
	v_pk_add_f32 v[52:53], v[52:53], 1.0 op_sel_hi:[1,0]
	v_pk_add_f32 v[54:55], v[54:55], 1.0 op_sel_hi:[1,0]
	v_rcp_f32_e64 v60, v60
	v_rcp_f32_e64 v61, v61
	v_rcp_f32_e64 v62, v62
	v_rcp_f32_e64 v63, v63
	v_rcp_f32_e64 v52, v52
	v_rcp_f32_e64 v53, v53
	v_rcp_f32_e64 v54, v54
	v_rcp_f32_e64 v55, v55
	v_pk_mul_f32 v[60:61], v[60:61], v[158:159] op_sel_hi:[1,0]
	v_pk_mul_f32 v[62:63], v[62:63], v[158:159] op_sel_hi:[1,0]
	v_pk_mul_f32 v[52:53], v[52:53], v[158:159] op_sel_hi:[1,0]
	v_pk_mul_f32 v[54:55], v[54:55], v[158:159] op_sel_hi:[1,0]
	v_cvt_pk_f16_f32 v148, v60, v61
	v_cvt_pk_f16_f32 v149, v62, v63
	v_cvt_pk_f16_f32 v150, v52, v53
	v_cvt_pk_f16_f32 v151, v54, v55
	global_store_dwordx4 v146, v[148:151], s[86:87]
	v_pk_add_f32 v[56:57], v[56:57], v[136:137]
	v_pk_add_f32 v[58:59], v[58:59], v[138:139]
	v_pk_add_f32 v[48:49], v[48:49], v[140:141]
	v_pk_add_f32 v[50:51], v[50:51], v[142:143]
	v_pk_mul_f32 v[56:57], v[56:57], v[144:145] op_sel_hi:[1,0]
	v_pk_mul_f32 v[58:59], v[58:59], v[144:145] op_sel_hi:[1,0]
	v_pk_mul_f32 v[48:49], v[48:49], v[144:145] op_sel_hi:[1,0]
	v_pk_mul_f32 v[50:51], v[50:51], v[144:145] op_sel_hi:[1,0]
	v_exp_f32_e64 v56, v56
	v_exp_f32_e64 v57, v57
	v_exp_f32_e64 v58, v58
	v_exp_f32_e64 v59, v59
	v_exp_f32_e64 v48, v48
	v_exp_f32_e64 v49, v49
	v_exp_f32_e64 v50, v50
	v_exp_f32_e64 v51, v51
	v_pk_add_f32 v[56:57], v[56:57], 1.0 op_sel_hi:[1,0]
	v_pk_add_f32 v[58:59], v[58:59], 1.0 op_sel_hi:[1,0]
	v_pk_add_f32 v[48:49], v[48:49], 1.0 op_sel_hi:[1,0]
	v_pk_add_f32 v[50:51], v[50:51], 1.0 op_sel_hi:[1,0]
	v_rcp_f32_e64 v56, v56
	v_rcp_f32_e64 v57, v57
	v_rcp_f32_e64 v58, v58
	v_rcp_f32_e64 v59, v59
	v_rcp_f32_e64 v48, v48
	v_rcp_f32_e64 v49, v49
	v_rcp_f32_e64 v50, v50
	v_rcp_f32_e64 v51, v51
	v_pk_mul_f32 v[56:57], v[56:57], v[158:159] op_sel_hi:[1,0]
	v_pk_mul_f32 v[58:59], v[58:59], v[158:159] op_sel_hi:[1,0]
	v_pk_mul_f32 v[48:49], v[48:49], v[158:159] op_sel_hi:[1,0]
	v_pk_mul_f32 v[50:51], v[50:51], v[158:159] op_sel_hi:[1,0]
	v_cvt_pk_f16_f32 v152, v56, v57
	v_cvt_pk_f16_f32 v153, v58, v59
	v_cvt_pk_f16_f32 v154, v48, v49
	v_cvt_pk_f16_f32 v155, v50, v51
	global_store_dwordx4 v146, v[152:155], s[86:87] offset:256
	v_add_u32_e32 v146, 0x4000, v146
	v_pk_add_f32 v[44:45], v[44:45], v[128:129]
	v_pk_add_f32 v[46:47], v[46:47], v[130:131]
	v_pk_add_f32 v[36:37], v[36:37], v[132:133]
	v_pk_add_f32 v[38:39], v[38:39], v[134:135]
	v_pk_mul_f32 v[44:45], v[44:45], v[144:145] op_sel_hi:[1,0]
	v_pk_mul_f32 v[46:47], v[46:47], v[144:145] op_sel_hi:[1,0]
	v_pk_mul_f32 v[36:37], v[36:37], v[144:145] op_sel_hi:[1,0]
	v_pk_mul_f32 v[38:39], v[38:39], v[144:145] op_sel_hi:[1,0]
	v_exp_f32_e64 v44, v44
	v_exp_f32_e64 v45, v45
	v_exp_f32_e64 v46, v46
	v_exp_f32_e64 v47, v47
	v_exp_f32_e64 v36, v36
	v_exp_f32_e64 v37, v37
	v_exp_f32_e64 v38, v38
	v_exp_f32_e64 v39, v39
	v_pk_add_f32 v[44:45], v[44:45], 1.0 op_sel_hi:[1,0]
	v_pk_add_f32 v[46:47], v[46:47], 1.0 op_sel_hi:[1,0]
	v_pk_add_f32 v[36:37], v[36:37], 1.0 op_sel_hi:[1,0]
	v_pk_add_f32 v[38:39], v[38:39], 1.0 op_sel_hi:[1,0]
	v_rcp_f32_e64 v44, v44
	v_rcp_f32_e64 v45, v45
	v_rcp_f32_e64 v46, v46
	v_rcp_f32_e64 v47, v47
	v_rcp_f32_e64 v36, v36
	v_rcp_f32_e64 v37, v37
	v_rcp_f32_e64 v38, v38
	v_rcp_f32_e64 v39, v39
	v_pk_mul_f32 v[44:45], v[44:45], v[158:159] op_sel_hi:[1,0]
	v_pk_mul_f32 v[46:47], v[46:47], v[158:159] op_sel_hi:[1,0]
	v_pk_mul_f32 v[36:37], v[36:37], v[158:159] op_sel_hi:[1,0]
	v_pk_mul_f32 v[38:39], v[38:39], v[158:159] op_sel_hi:[1,0]
	v_cvt_pk_f16_f32 v148, v44, v45
	v_cvt_pk_f16_f32 v149, v46, v47
	v_cvt_pk_f16_f32 v150, v36, v37
	v_cvt_pk_f16_f32 v151, v38, v39
	global_store_dwordx4 v146, v[148:151], s[86:87]
	v_pk_add_f32 v[40:41], v[40:41], v[136:137]
	v_pk_add_f32 v[42:43], v[42:43], v[138:139]
	v_pk_add_f32 v[32:33], v[32:33], v[140:141]
	v_pk_add_f32 v[34:35], v[34:35], v[142:143]
	v_pk_mul_f32 v[40:41], v[40:41], v[144:145] op_sel_hi:[1,0]
	v_pk_mul_f32 v[42:43], v[42:43], v[144:145] op_sel_hi:[1,0]
	v_pk_mul_f32 v[32:33], v[32:33], v[144:145] op_sel_hi:[1,0]
	v_pk_mul_f32 v[34:35], v[34:35], v[144:145] op_sel_hi:[1,0]
	v_exp_f32_e64 v40, v40
	v_exp_f32_e64 v41, v41
	v_exp_f32_e64 v42, v42
	v_exp_f32_e64 v43, v43
	v_exp_f32_e64 v32, v32
	v_exp_f32_e64 v33, v33
	v_exp_f32_e64 v34, v34
	v_exp_f32_e64 v35, v35
	v_pk_add_f32 v[40:41], v[40:41], 1.0 op_sel_hi:[1,0]
	v_pk_add_f32 v[42:43], v[42:43], 1.0 op_sel_hi:[1,0]
	v_pk_add_f32 v[32:33], v[32:33], 1.0 op_sel_hi:[1,0]
	v_pk_add_f32 v[34:35], v[34:35], 1.0 op_sel_hi:[1,0]
	v_rcp_f32_e64 v40, v40
	v_rcp_f32_e64 v41, v41
	v_rcp_f32_e64 v42, v42
	v_rcp_f32_e64 v43, v43
	v_rcp_f32_e64 v32, v32
	v_rcp_f32_e64 v33, v33
	v_rcp_f32_e64 v34, v34
	v_rcp_f32_e64 v35, v35
	v_pk_mul_f32 v[40:41], v[40:41], v[158:159] op_sel_hi:[1,0]
	v_pk_mul_f32 v[42:43], v[42:43], v[158:159] op_sel_hi:[1,0]
	v_pk_mul_f32 v[32:33], v[32:33], v[158:159] op_sel_hi:[1,0]
	v_pk_mul_f32 v[34:35], v[34:35], v[158:159] op_sel_hi:[1,0]
	v_cvt_pk_f16_f32 v152, v40, v41
	v_cvt_pk_f16_f32 v153, v42, v43
	v_cvt_pk_f16_f32 v154, v32, v33
	v_cvt_pk_f16_f32 v155, v34, v35
	global_store_dwordx4 v146, v[152:155], s[86:87] offset:256
	v_add_u32_e32 v146, 0x4000, v146
	v_pk_add_f32 v[28:29], v[28:29], v[128:129]
	v_pk_add_f32 v[30:31], v[30:31], v[130:131]
	v_pk_add_f32 v[20:21], v[20:21], v[132:133]
	v_pk_add_f32 v[22:23], v[22:23], v[134:135]
	v_pk_mul_f32 v[28:29], v[28:29], v[144:145] op_sel_hi:[1,0]
	v_pk_mul_f32 v[30:31], v[30:31], v[144:145] op_sel_hi:[1,0]
	v_pk_mul_f32 v[20:21], v[20:21], v[144:145] op_sel_hi:[1,0]
	v_pk_mul_f32 v[22:23], v[22:23], v[144:145] op_sel_hi:[1,0]
	v_exp_f32_e64 v28, v28
	v_exp_f32_e64 v29, v29
	v_exp_f32_e64 v30, v30
	v_exp_f32_e64 v31, v31
	v_exp_f32_e64 v20, v20
	v_exp_f32_e64 v21, v21
	v_exp_f32_e64 v22, v22
	v_exp_f32_e64 v23, v23
	v_pk_add_f32 v[28:29], v[28:29], 1.0 op_sel_hi:[1,0]
	v_pk_add_f32 v[30:31], v[30:31], 1.0 op_sel_hi:[1,0]
	v_pk_add_f32 v[20:21], v[20:21], 1.0 op_sel_hi:[1,0]
	v_pk_add_f32 v[22:23], v[22:23], 1.0 op_sel_hi:[1,0]
	v_rcp_f32_e64 v28, v28
	v_rcp_f32_e64 v29, v29
	v_rcp_f32_e64 v30, v30
	v_rcp_f32_e64 v31, v31
	v_rcp_f32_e64 v20, v20
	v_rcp_f32_e64 v21, v21
	v_rcp_f32_e64 v22, v22
	v_rcp_f32_e64 v23, v23
	v_pk_mul_f32 v[28:29], v[28:29], v[158:159] op_sel_hi:[1,0]
	v_pk_mul_f32 v[30:31], v[30:31], v[158:159] op_sel_hi:[1,0]
	v_pk_mul_f32 v[20:21], v[20:21], v[158:159] op_sel_hi:[1,0]
	v_pk_mul_f32 v[22:23], v[22:23], v[158:159] op_sel_hi:[1,0]
	v_cvt_pk_f16_f32 v148, v28, v29
	v_cvt_pk_f16_f32 v149, v30, v31
	v_cvt_pk_f16_f32 v150, v20, v21
	v_cvt_pk_f16_f32 v151, v22, v23
	global_store_dwordx4 v146, v[148:151], s[86:87]
	v_pk_add_f32 v[24:25], v[24:25], v[136:137]
	v_pk_add_f32 v[26:27], v[26:27], v[138:139]
	v_pk_add_f32 v[16:17], v[16:17], v[140:141]
	v_pk_add_f32 v[18:19], v[18:19], v[142:143]
	v_pk_mul_f32 v[24:25], v[24:25], v[144:145] op_sel_hi:[1,0]
	v_pk_mul_f32 v[26:27], v[26:27], v[144:145] op_sel_hi:[1,0]
	v_pk_mul_f32 v[16:17], v[16:17], v[144:145] op_sel_hi:[1,0]
	v_pk_mul_f32 v[18:19], v[18:19], v[144:145] op_sel_hi:[1,0]
	v_exp_f32_e64 v24, v24
	v_exp_f32_e64 v25, v25
	v_exp_f32_e64 v26, v26
	v_exp_f32_e64 v27, v27
	v_exp_f32_e64 v16, v16
	v_exp_f32_e64 v17, v17
	v_exp_f32_e64 v18, v18
	v_exp_f32_e64 v19, v19
	v_pk_add_f32 v[24:25], v[24:25], 1.0 op_sel_hi:[1,0]
	v_pk_add_f32 v[26:27], v[26:27], 1.0 op_sel_hi:[1,0]
	v_pk_add_f32 v[16:17], v[16:17], 1.0 op_sel_hi:[1,0]
	v_pk_add_f32 v[18:19], v[18:19], 1.0 op_sel_hi:[1,0]
	v_rcp_f32_e64 v24, v24
	v_rcp_f32_e64 v25, v25
	v_rcp_f32_e64 v26, v26
	v_rcp_f32_e64 v27, v27
	v_rcp_f32_e64 v16, v16
	v_rcp_f32_e64 v17, v17
	v_rcp_f32_e64 v18, v18
	v_rcp_f32_e64 v19, v19
	v_pk_mul_f32 v[24:25], v[24:25], v[158:159] op_sel_hi:[1,0]
	v_pk_mul_f32 v[26:27], v[26:27], v[158:159] op_sel_hi:[1,0]
	v_pk_mul_f32 v[16:17], v[16:17], v[158:159] op_sel_hi:[1,0]
	v_pk_mul_f32 v[18:19], v[18:19], v[158:159] op_sel_hi:[1,0]
	v_cvt_pk_f16_f32 v152, v24, v25
	v_cvt_pk_f16_f32 v153, v26, v27
	v_cvt_pk_f16_f32 v154, v16, v17
	v_cvt_pk_f16_f32 v155, v18, v19
	global_store_dwordx4 v146, v[152:155], s[86:87] offset:256
	v_add_u32_e32 v146, 0x4000, v146
	v_pk_add_f32 v[12:13], v[12:13], v[128:129]
	v_pk_add_f32 v[14:15], v[14:15], v[130:131]
	v_pk_add_f32 v[4:5], v[4:5], v[132:133]
	v_pk_add_f32 v[6:7], v[6:7], v[134:135]
	v_pk_mul_f32 v[12:13], v[12:13], v[144:145] op_sel_hi:[1,0]
	v_pk_mul_f32 v[14:15], v[14:15], v[144:145] op_sel_hi:[1,0]
	v_pk_mul_f32 v[4:5], v[4:5], v[144:145] op_sel_hi:[1,0]
	v_pk_mul_f32 v[6:7], v[6:7], v[144:145] op_sel_hi:[1,0]
	v_exp_f32_e64 v12, v12
	v_exp_f32_e64 v13, v13
	v_exp_f32_e64 v14, v14
	v_exp_f32_e64 v15, v15
	v_exp_f32_e64 v4, v4
	v_exp_f32_e64 v5, v5
	v_exp_f32_e64 v6, v6
	v_exp_f32_e64 v7, v7
	v_pk_add_f32 v[12:13], v[12:13], 1.0 op_sel_hi:[1,0]
	v_pk_add_f32 v[14:15], v[14:15], 1.0 op_sel_hi:[1,0]
	v_pk_add_f32 v[4:5], v[4:5], 1.0 op_sel_hi:[1,0]
	v_pk_add_f32 v[6:7], v[6:7], 1.0 op_sel_hi:[1,0]
	v_rcp_f32_e64 v12, v12
	v_rcp_f32_e64 v13, v13
	v_rcp_f32_e64 v14, v14
	v_rcp_f32_e64 v15, v15
	v_rcp_f32_e64 v4, v4
	v_rcp_f32_e64 v5, v5
	v_rcp_f32_e64 v6, v6
	v_rcp_f32_e64 v7, v7
	v_pk_mul_f32 v[12:13], v[12:13], v[158:159] op_sel_hi:[1,0]
	v_pk_mul_f32 v[14:15], v[14:15], v[158:159] op_sel_hi:[1,0]
	v_pk_mul_f32 v[4:5], v[4:5], v[158:159] op_sel_hi:[1,0]
	v_pk_mul_f32 v[6:7], v[6:7], v[158:159] op_sel_hi:[1,0]
	v_cvt_pk_f16_f32 v148, v12, v13
	v_cvt_pk_f16_f32 v149, v14, v15
	v_cvt_pk_f16_f32 v150, v4, v5
	v_cvt_pk_f16_f32 v151, v6, v7
	global_store_dwordx4 v146, v[148:151], s[86:87]
	v_pk_add_f32 v[8:9], v[8:9], v[136:137]
	v_pk_add_f32 v[10:11], v[10:11], v[138:139]
	v_pk_add_f32 v[0:1], v[0:1], v[140:141]
	v_pk_add_f32 v[2:3], v[2:3], v[142:143]
	v_pk_mul_f32 v[8:9], v[8:9], v[144:145] op_sel_hi:[1,0]
	v_pk_mul_f32 v[10:11], v[10:11], v[144:145] op_sel_hi:[1,0]
	v_pk_mul_f32 v[0:1], v[0:1], v[144:145] op_sel_hi:[1,0]
	v_pk_mul_f32 v[2:3], v[2:3], v[144:145] op_sel_hi:[1,0]
	v_exp_f32_e64 v8, v8
	v_exp_f32_e64 v9, v9
	v_exp_f32_e64 v10, v10
	v_exp_f32_e64 v11, v11
	v_exp_f32_e64 v0, v0
	v_exp_f32_e64 v1, v1
	v_exp_f32_e64 v2, v2
	v_exp_f32_e64 v3, v3
	v_pk_add_f32 v[8:9], v[8:9], 1.0 op_sel_hi:[1,0]
	v_pk_add_f32 v[10:11], v[10:11], 1.0 op_sel_hi:[1,0]
	v_pk_add_f32 v[0:1], v[0:1], 1.0 op_sel_hi:[1,0]
	v_pk_add_f32 v[2:3], v[2:3], 1.0 op_sel_hi:[1,0]
	v_rcp_f32_e64 v8, v8
	v_rcp_f32_e64 v9, v9
	v_rcp_f32_e64 v10, v10
	v_rcp_f32_e64 v11, v11
	v_rcp_f32_e64 v0, v0
	v_rcp_f32_e64 v1, v1
	v_rcp_f32_e64 v2, v2
	v_rcp_f32_e64 v3, v3
	v_pk_mul_f32 v[8:9], v[8:9], v[158:159] op_sel_hi:[1,0]
	v_pk_mul_f32 v[10:11], v[10:11], v[158:159] op_sel_hi:[1,0]
	v_pk_mul_f32 v[0:1], v[0:1], v[158:159] op_sel_hi:[1,0]
	v_pk_mul_f32 v[2:3], v[2:3], v[158:159] op_sel_hi:[1,0]
	v_cvt_pk_f16_f32 v152, v8, v9
	v_cvt_pk_f16_f32 v153, v10, v11
	v_cvt_pk_f16_f32 v154, v0, v1
	v_cvt_pk_f16_f32 v155, v2, v3
	global_store_dwordx4 v146, v[152:155], s[86:87] offset:256
	s_branch .Lepi3_done
